# v44 stack + prompt attention key-tile loop: the four K-fragment LDS reads issued together with counted lgkmcnt
# speedup vs baseline: 1.0126x; 1.0054x over previous
; #define LAS __attribute__((address_space(3)))
; #define MFMA32(a, b, c) __builtin_amdgcn_mfma_f32_32x32x16_bf16((a), (b), (c), 0, 0, 0)
; __device__ __forceinline__ int crow(int reg, int hh) { return (reg & 3) + 8 * (reg >> 2) + 4 * hh; }
; __device__ __forceinline__ void attn_mfma_phase(LAS unsigned char* lds, const bf16* QKVb, bf16* OPART, float2* ML, int tid, int wave, int lane) {
;     ...
;             const LAS unsigned char* kp = kimg + (jb + i) * RSK + 16 * hh;
;             f32x16 s;
; #pragma unroll
;             for (int e = 0; e < 16; ++e) s[e] = 0.f;
; #pragma unroll
;             for (int ks = 0; ks < 4; ++ks) { const bf16x8 kf = *(const LAS bf16x8*)(kp + 32 * ks); s = MFMA32(kf, qf[ks], s); }
;             float tm = -1e30f;
;             if (kt == 0) {
; #pragma unroll
;                 for (int e = 0; e < 16; ++e) s[e] = crow(e, hh) < i ? -1e30f : s[e];
.LBB0_1041:
	v_add_u32_e32 v38, 0, v175
	ds_read_b128 v[34:37], v38
	ds_read_b128 v[42:45], v38 offset:32
	ds_read_b128 v[46:49], v38 offset:64
	ds_read_b128 v[38:41], v38 offset:96
	s_cmp_gt_i32 s87, 3
	s_mov_b64 s[92:93], -1
	s_waitcnt lgkmcnt(3)
	v_mfma_f32_32x32x16_bf16 v[50:65], v[34:37], v[114:117], 0
	s_waitcnt lgkmcnt(2)
	v_mfma_f32_32x32x16_bf16 v[50:65], v[42:45], v[118:121], v[50:65]
	s_waitcnt lgkmcnt(1)
	v_mfma_f32_32x32x16_bf16 v[50:65], v[46:49], v[122:125], v[50:65]
	s_waitcnt lgkmcnt(0)
	v_mfma_f32_32x32x16_bf16 v[50:65], v[38:41], v[126:129], v[50:65]
	s_cbranch_scc0 .LBB0_1043
	s_nop 10
	v_cndmask_b32_e64 v34, v50, v174, s[6:7]
	v_cndmask_b32_e64 v35, v174, v51, s[8:9]
	v_cndmask_b32_e64 v36, v52, v174, s[10:11]
	v_cndmask_b32_e64 v37, v53, v174, s[12:13]
	v_cndmask_b32_e64 v38, v54, v174, s[14:15]
	v_cndmask_b32_e64 v39, v55, v174, s[16:17]
	v_cndmask_b32_e64 v40, v56, v174, s[18:19]
	v_cndmask_b32_e64 v41, v57, v174, s[20:21]
	v_cndmask_b32_e64 v42, v58, v174, s[22:23]
	v_cndmask_b32_e64 v43, v59, v174, s[24:25]
	v_cndmask_b32_e64 v44, v60, v174, s[26:27]
	v_cndmask_b32_e64 v45, v61, v174, s[28:29]
	v_cndmask_b32_e64 v46, v62, v174, s[30:31]
	v_cndmask_b32_e64 v47, v63, v174, s[34:35]
	v_cndmask_b32_e64 v48, v64, v174, s[36:37]
	v_cndmask_b32_e64 v49, v65, v174, s[38:39]
	s_mov_b64 s[92:93], 0
